# adds: phase W w_in transpose tile loads (8 source + 8 gain) issued together and waited once instead of one at a time
# speedup vs baseline: 1.0401x; 1.0101x over previous
; DI int opaque_bid() { int b = blockIdx.x; asm volatile("" : "+s"(b)); return b; }
; DI void transpose_job(const float* __restrict__ src, const float* __restrict__ gain, u16* __restrict__ dst, int K, int N, bool q8 = false) {
;     ...
;   for (int tile = opaque_bid(); tile < nk * nn; tile += gridDim.x) {
;     const int k0 = (tile / nn) << 6, n0 = (tile % nn) << 6;
; #pragma unroll
;     for (int i = 0; i < 8; ++i) {
;       int e = tid + i * NTHREADS, kk = e >> 6, c = e & 63;
;       float v = src[(size_t)(k0 + kk) * N + n0 + c];
;       if (gain) v *= gain[k0 + kk];
;       t[kk * 65 + c] = v;
;     }
;     __syncthreads();
; #pragma unroll
;     for (int i = 0; i < 8; ++i) {
;       int e = tid + i * NTHREADS, c = e >> 6, kk = e & 63;
;       if (q8) ((u8*)dst)[(size_t)(n0 + c) * K + k0 + kk] = (u8)(pk4_fp8(t[kk * 65 + c] * WQ_SCALE, 0.f, 0.f, 0.f) & 0xffu);
;       else dst[(size_t)(n0 + c) * K + k0 + kk] = (u16)(pk2(t[kk * 65 + c], 0.f) & 0xffffu);
;     }
;     __syncthreads();
.LBB0_586:
	s_waitcnt lgkmcnt(0)
	s_barrier
	ds_read_b32 v8, v17
	v_mov_b32_e32 v33, 0
	s_ashr_i32 s39, s38, 31
	v_lshl_add_u64 v[6:7], v[4:5], 0, s[38:39]
	s_add_i32 s51, s51, s52
	s_waitcnt lgkmcnt(0)
	v_mul_f32_e32 v8, 0x42000000, v8
	v_cvt_pk_fp8_f32 v33, v8, 0
	v_add_u32_e32 v8, s36, v0
	v_ashrrev_i32_e32 v9, 31, v8
	v_lshlrev_b64 v[8:9], 10, v[8:9]
	v_cvt_pk_fp8_f32 v33, 0, 0 op_sel:[0,0,1]
	v_lshl_add_u64 v[8:9], v[6:7], 0, v[8:9]
	s_add_i32 s53, s53, s56
	s_cmpk_lt_i32 s51, 0x840
	global_store_byte v[8:9], v33, off
	ds_read_b32 v8, v18
	v_mov_b32_e32 v33, 0
	s_waitcnt lgkmcnt(0)
	v_mul_f32_e32 v8, 0x42000000, v8
	v_cvt_pk_fp8_f32 v33, v8, 0
	v_add_u32_e32 v8, s36, v10
	v_ashrrev_i32_e32 v9, 31, v8
	v_lshlrev_b64 v[8:9], 10, v[8:9]
	v_cvt_pk_fp8_f32 v33, 0, 0 op_sel:[0,0,1]
	v_lshl_add_u64 v[8:9], v[6:7], 0, v[8:9]
	global_store_byte v[8:9], v33, off
	ds_read_b32 v8, v19
	v_mov_b32_e32 v33, 0
	s_waitcnt lgkmcnt(0)
	v_mul_f32_e32 v8, 0x42000000, v8
	v_cvt_pk_fp8_f32 v33, v8, 0
	v_add_u32_e32 v8, s36, v11
	v_ashrrev_i32_e32 v9, 31, v8
	v_lshlrev_b64 v[8:9], 10, v[8:9]
	v_cvt_pk_fp8_f32 v33, 0, 0 op_sel:[0,0,1]
	v_lshl_add_u64 v[8:9], v[6:7], 0, v[8:9]
	global_store_byte v[8:9], v33, off
	ds_read_b32 v8, v20
	v_mov_b32_e32 v33, 0
	s_waitcnt lgkmcnt(0)
	v_mul_f32_e32 v8, 0x42000000, v8
	v_cvt_pk_fp8_f32 v33, v8, 0
	v_add_u32_e32 v8, s36, v12
	v_ashrrev_i32_e32 v9, 31, v8
	v_lshlrev_b64 v[8:9], 10, v[8:9]
	v_cvt_pk_fp8_f32 v33, 0, 0 op_sel:[0,0,1]
	v_lshl_add_u64 v[8:9], v[6:7], 0, v[8:9]
	global_store_byte v[8:9], v33, off
	ds_read_b32 v8, v21
	v_mov_b32_e32 v33, 0
	s_waitcnt lgkmcnt(0)
	v_mul_f32_e32 v8, 0x42000000, v8
	v_cvt_pk_fp8_f32 v33, v8, 0
	v_add_u32_e32 v8, s36, v13
	v_ashrrev_i32_e32 v9, 31, v8
	v_lshlrev_b64 v[8:9], 10, v[8:9]
	v_cvt_pk_fp8_f32 v33, 0, 0 op_sel:[0,0,1]
	v_lshl_add_u64 v[8:9], v[6:7], 0, v[8:9]
	global_store_byte v[8:9], v33, off
	ds_read_b32 v8, v22
	v_mov_b32_e32 v33, 0
	s_waitcnt lgkmcnt(0)
	v_mul_f32_e32 v8, 0x42000000, v8
	v_cvt_pk_fp8_f32 v33, v8, 0
	v_add_u32_e32 v8, s36, v14
	v_ashrrev_i32_e32 v9, 31, v8
	v_lshlrev_b64 v[8:9], 10, v[8:9]
	v_cvt_pk_fp8_f32 v33, 0, 0 op_sel:[0,0,1]
	v_lshl_add_u64 v[8:9], v[6:7], 0, v[8:9]
	global_store_byte v[8:9], v33, off
	ds_read_b32 v8, v23
	v_mov_b32_e32 v33, 0
	s_waitcnt lgkmcnt(0)
	v_mul_f32_e32 v8, 0x42000000, v8
	v_cvt_pk_fp8_f32 v33, v8, 0
	v_add_u32_e32 v8, s36, v15
	v_ashrrev_i32_e32 v9, 31, v8
	v_lshlrev_b64 v[8:9], 10, v[8:9]
	v_cvt_pk_fp8_f32 v33, 0, 0 op_sel:[0,0,1]
	v_lshl_add_u64 v[8:9], v[6:7], 0, v[8:9]
	global_store_byte v[8:9], v33, off
	ds_read_b32 v8, v24
	v_mov_b32_e32 v33, 0
	s_waitcnt lgkmcnt(0)
	v_mul_f32_e32 v8, 0x42000000, v8
	v_cvt_pk_fp8_f32 v33, v8, 0
	v_add_u32_e32 v8, s36, v16
	v_ashrrev_i32_e32 v9, 31, v8
	v_lshlrev_b64 v[8:9], 10, v[8:9]
	v_cvt_pk_fp8_f32 v33, 0, 0 op_sel:[0,0,1]
	v_lshl_add_u64 v[6:7], v[6:7], 0, v[8:9]
	global_store_byte v[6:7], v33, off
	s_barrier
	s_cbranch_scc0 .LBB0_603
.LBB0_587:
	s_mul_hi_i32 s4, s51, 0x3e0f83e1
	s_lshr_b32 s5, s4, 31
	s_ashr_i32 s4, s4, 5
	s_add_i32 s4, s4, s5
	s_lshl_b32 s38, s4, 6
	s_mulk_i32 s4, 0xdf00
	s_add_i32 s36, s53, s4
	s_ashr_i32 s37, s36, 31
	v_lshl_add_u64 v[6:7], s[36:37], 2, v[2:3]
	v_add_u32_e32 v40, s38, v0
	v_mad_i64_i32 v[34:35], s[58:59], v40, s33, v[6:7]
	global_load_dword v56, v[34:35], off
	v_add_u32_e32 v42, s38, v10
	v_mad_i64_i32 v[34:35], s[58:59], v42, s33, v[6:7]
	global_load_dword v57, v[34:35], off
	v_add_u32_e32 v44, s38, v11
	v_mad_i64_i32 v[34:35], s[58:59], v44, s33, v[6:7]
	global_load_dword v58, v[34:35], off
	v_add_u32_e32 v46, s38, v12
	v_mad_i64_i32 v[34:35], s[58:59], v46, s33, v[6:7]
	global_load_dword v59, v[34:35], off
	v_add_u32_e32 v48, s38, v13
	v_mad_i64_i32 v[34:35], s[58:59], v48, s33, v[6:7]
	global_load_dword v60, v[34:35], off
	v_add_u32_e32 v50, s38, v14
	v_mad_i64_i32 v[34:35], s[58:59], v50, s33, v[6:7]
	global_load_dword v61, v[34:35], off
	v_add_u32_e32 v52, s38, v15
	v_mad_i64_i32 v[34:35], s[58:59], v52, s33, v[6:7]
	global_load_dword v62, v[34:35], off
	v_add_u32_e32 v54, s38, v16
	v_mad_i64_i32 v[34:35], s[58:59], v54, s33, v[6:7]
	global_load_dword v63, v[34:35], off
	s_andn2_b64 vcc, exec, s[24:25]
	s_cbranch_vccnz .Lw587_nogain
	v_ashrrev_i32_e32 v41, 31, v40
	v_lshl_add_u64 v[40:41], v[40:41], 2, s[34:35]
	global_load_dword v64, v[40:41], off
	v_ashrrev_i32_e32 v43, 31, v42
	v_lshl_add_u64 v[42:43], v[42:43], 2, s[34:35]
	global_load_dword v65, v[42:43], off
	v_ashrrev_i32_e32 v45, 31, v44
	v_lshl_add_u64 v[44:45], v[44:45], 2, s[34:35]
	global_load_dword v66, v[44:45], off
	v_ashrrev_i32_e32 v47, 31, v46
	v_lshl_add_u64 v[46:47], v[46:47], 2, s[34:35]
	global_load_dword v67, v[46:47], off
	v_ashrrev_i32_e32 v49, 31, v48
	v_lshl_add_u64 v[48:49], v[48:49], 2, s[34:35]
	global_load_dword v68, v[48:49], off
	v_ashrrev_i32_e32 v51, 31, v50
	v_lshl_add_u64 v[50:51], v[50:51], 2, s[34:35]
	global_load_dword v69, v[50:51], off
	v_ashrrev_i32_e32 v53, 31, v52
	v_lshl_add_u64 v[52:53], v[52:53], 2, s[34:35]
	global_load_dword v70, v[52:53], off
	v_ashrrev_i32_e32 v55, 31, v54
	v_lshl_add_u64 v[54:55], v[54:55], 2, s[34:35]
	global_load_dword v71, v[54:55], off
	s_waitcnt vmcnt(0)
	v_mul_f32_e32 v56, v56, v64
	v_mul_f32_e32 v57, v57, v65
	v_mul_f32_e32 v58, v58, v66
	v_mul_f32_e32 v59, v59, v67
	v_mul_f32_e32 v60, v60, v68
	v_mul_f32_e32 v61, v61, v69
	v_mul_f32_e32 v62, v62, v70
	v_mul_f32_e32 v63, v63, v71
.Lw587_nogain:
	s_waitcnt vmcnt(0)
	ds_write_b32 v25, v56
	ds_write_b32 v26, v57
	ds_write_b32 v27, v58
	ds_write_b32 v28, v59
	ds_write_b32 v29, v60
	ds_write_b32 v30, v61
	ds_write_b32 v31, v62
	ds_write_b32 v32, v63
	s_branch .LBB0_586

; #define LOAD_PARAMS() KParams kq_ = (KParams)__builtin_amdgcn_kernarg_segment_ptr(); asm volatile("" : "+s"(kq_)); const Params p = *kq_
; template <int CT>
; __global__ void __launch_bounds__(NTHREADS) mega_kernel(Params p) {
;     ...
; #pragma unroll 1
;   for (int ph = 0; ph < nph; ++ph) {
;     run_phase<CT>(ph);
;     if (ph + 1 < nph) {
;       LOAD_PARAMS();
;       xcd_barrier((unsigned*)(p.ws + WS<CT>::bar), x, nloc, nx, k);
;       ++k;
;     }
;   }
; }
.LBB0_726:
	s_endpgm
	s_nop 0
	s_nop 0
	s_nop 0
	s_nop 0
	s_nop 0
	s_nop 0
	s_nop 0
	s_nop 0
	s_nop 0
	s_nop 0
	s_nop 0
	s_nop 0
	s_nop 0
	s_nop 0
	s_nop 0
	s_nop 0
	s_nop 0
	s_nop 0
	s_nop 0
	s_nop 0
	s_nop 0
	s_nop 0
	s_nop 0
	s_nop 0
	s_nop 0
	s_nop 0
	s_nop 0
	s_nop 0
	s_nop 0
	s_nop 0
	s_nop 0
	s_nop 0
	s_nop 0
	s_nop 0
	s_nop 0
	s_nop 0
	s_nop 0
	s_nop 0
	s_nop 0
	s_nop 0
	s_nop 0
	s_nop 0
	s_nop 0
	s_nop 0
	s_nop 0
	s_nop 0
	s_nop 0
	s_endpgm
